# b6 + attention NOMAX loops: row-sum adds moved under the QK MFMA burst (exp outputs renamed, E waves deferred one tile), same add order
# speedup vs baseline: 1.0065x; 1.0022x over previous
.LBB0_629:
	s_bitcmp1_b32 s8, 0
	s_mov_b32 s41, s22
	s_cselect_b32 s22, 0x2400, 0
	s_mul_i32 s45, s41, 0x3400
	v_add_u32_e32 v91, s22, v90
	v_add_u32_e32 v173, s45, v89
	ds_read_b128 v[92:95], v91 offset:39936
	ds_read_b128 v[96:99], v91 offset:39968
	ds_read_b128 v[100:103], v91 offset:44544
	ds_read_b128 v[104:107], v91 offset:44576
	ds_read_b128 v[108:111], v91 offset:40000
	ds_read_b128 v[112:115], v91 offset:40032
	ds_read_b128 v[116:119], v91 offset:44608
	ds_read_b128 v[120:123], v91 offset:44640
	ds_read_b128 v[124:127], v173
	ds_read_b128 v[128:131], v173 offset:32
	ds_read_b128 v[132:135], v173 offset:6656
	ds_read_b128 v[136:139], v173 offset:6688
	ds_read_b128 v[140:143], v173 offset:64
	ds_read_b128 v[144:147], v173 offset:96
	ds_read_b128 v[148:151], v173 offset:6720
	ds_read_b128 v[152:155], v173 offset:6752
	ds_read_b128 v[156:159], v173 offset:128
	ds_read_b128 v[160:163], v173 offset:160
	ds_read_b128 v[164:167], v173 offset:6784
	ds_read_b128 v[174:177], v173 offset:6816
	s_mov_b32 s22, s44
	s_add_i32 s8, s8, 1
	v_exp_f32_e32 v184, v48
	v_exp_f32_e32 v185, v49
	v_exp_f32_e32 v186, v50
	v_exp_f32_e32 v187, v51
	v_exp_f32_e32 v188, v52
	v_exp_f32_e32 v189, v53
	v_exp_f32_e32 v190, v54
	v_exp_f32_e32 v191, v55
	v_exp_f32_e32 v91, v32
	v_exp_f32_e32 v173, v33
	v_exp_f32_e32 v178, v34
	v_exp_f32_e32 v179, v35
	v_cvt_pk_bf16_f32 v32, v184, v185
	v_cvt_pk_bf16_f32 v33, v186, v187
	v_cvt_pk_bf16_f32 v34, v188, v189
	v_cvt_pk_bf16_f32 v35, v190, v191
	v_exp_f32_e32 v192, v56
	v_exp_f32_e32 v193, v57
	s_waitcnt lgkmcnt(14)
	v_mfma_f32_32x32x16_bf16 v[16:31], v[92:95], v[32:35], v[16:31]
	v_exp_f32_e32 v194, v58
	v_exp_f32_e32 v195, v59
	v_exp_f32_e32 v196, v60
	v_exp_f32_e32 v197, v61
	v_exp_f32_e32 v198, v62
	v_exp_f32_e32 v199, v63
	v_exp_f32_e32 v180, v36
	v_mfma_f32_32x32x16_bf16 v[0:15], v[100:103], v[32:35], v[0:15]
	v_exp_f32_e32 v181, v37
	v_exp_f32_e32 v182, v38
	v_exp_f32_e32 v183, v39
	v_cvt_pk_bf16_f32 v32, v192, v193
	v_cvt_pk_bf16_f32 v33, v194, v195
	v_cvt_pk_bf16_f32 v34, v196, v197
	v_cvt_pk_bf16_f32 v35, v198, v199
	v_exp_f32_e32 v200, v40
	v_exp_f32_e32 v201, v41
	v_mfma_f32_32x32x16_bf16 v[16:31], v[96:99], v[32:35], v[16:31]
	v_exp_f32_e32 v202, v42
	v_exp_f32_e32 v203, v43
	v_exp_f32_e32 v204, v44
	v_exp_f32_e32 v205, v45
	v_exp_f32_e32 v206, v46
	v_exp_f32_e32 v207, v47
	v_cvt_pk_bf16_f32 v36, v91, v173
	v_mfma_f32_32x32x16_bf16 v[0:15], v[104:107], v[32:35], v[0:15]
	v_cvt_pk_bf16_f32 v37, v178, v179
	v_cvt_pk_bf16_f32 v38, v180, v181
	v_cvt_pk_bf16_f32 v39, v182, v183
	v_add_f32_e32 v208, v184, v88
	v_add_f32_e32 v208, v91, v208
	v_mfma_f32_32x32x16_bf16 v[16:31], v[108:111], v[36:39], v[16:31]
	s_waitcnt lgkmcnt(13)
	v_mfma_f32_32x32x16_bf16 v[0:15], v[116:119], v[36:39], v[0:15]
	v_cvt_pk_bf16_f32 v32, v200, v201
	v_cvt_pk_bf16_f32 v33, v202, v203
	v_cvt_pk_bf16_f32 v34, v204, v205
	v_cvt_pk_bf16_f32 v35, v206, v207
	v_add_f32_e32 v208, v185, v208
	v_add_f32_e32 v208, v173, v208
	v_mfma_f32_32x32x16_bf16 v[16:31], v[112:115], v[32:35], v[16:31]
	s_waitcnt lgkmcnt(12)
	v_mfma_f32_32x32x16_bf16 v[0:15], v[120:123], v[32:35], v[0:15]
	s_setprio 1
	s_waitcnt lgkmcnt(11)
	v_mfma_f32_32x32x16_bf16 v[48:63], v[124:127], v[64:67], 0
	v_add_f32_e32 v208, v186, v208
	v_add_f32_e32 v208, v178, v208
	v_add_f32_e32 v208, v187, v208
	s_waitcnt lgkmcnt(9)
	v_mfma_f32_32x32x16_bf16 v[32:47], v[132:135], v[64:67], 0
	v_add_f32_e32 v208, v179, v208
	v_add_f32_e32 v208, v188, v208
	v_add_f32_e32 v208, v180, v208
	v_mfma_f32_32x32x16_bf16 v[48:63], v[128:131], v[68:71], v[48:63]
	v_add_f32_e32 v208, v189, v208
	v_add_f32_e32 v208, v181, v208
	v_add_f32_e32 v208, v190, v208
	s_waitcnt lgkmcnt(8)
	v_mfma_f32_32x32x16_bf16 v[32:47], v[136:139], v[68:71], v[32:47]
	v_add_f32_e32 v208, v182, v208
	v_add_f32_e32 v208, v191, v208
	v_add_f32_e32 v208, v183, v208
	s_waitcnt lgkmcnt(7)
	v_mfma_f32_32x32x16_bf16 v[48:63], v[140:143], v[72:75], v[48:63]
	v_add_f32_e32 v208, v192, v208
	v_add_f32_e32 v208, v200, v208
	s_waitcnt lgkmcnt(5)
	v_mfma_f32_32x32x16_bf16 v[32:47], v[148:151], v[72:75], v[32:47]
	v_add_f32_e32 v208, v193, v208
	v_add_f32_e32 v208, v201, v208
	v_mfma_f32_32x32x16_bf16 v[48:63], v[144:147], v[76:79], v[48:63]
	v_add_f32_e32 v208, v194, v208
	v_add_f32_e32 v208, v202, v208
	s_waitcnt lgkmcnt(4)
	v_mfma_f32_32x32x16_bf16 v[32:47], v[152:155], v[76:79], v[32:47]
	v_add_f32_e32 v208, v195, v208
	v_add_f32_e32 v208, v203, v208
	s_waitcnt lgkmcnt(3)
	v_mfma_f32_32x32x16_bf16 v[48:63], v[156:159], v[80:83], v[48:63]
	v_add_f32_e32 v208, v196, v208
	v_add_f32_e32 v208, v204, v208
	s_waitcnt lgkmcnt(1)
	v_mfma_f32_32x32x16_bf16 v[32:47], v[164:167], v[80:83], v[32:47]
	v_add_f32_e32 v208, v197, v208
	v_add_f32_e32 v208, v205, v208
	v_mfma_f32_32x32x16_bf16 v[48:63], v[160:163], v[84:87], v[48:63]
	v_add_f32_e32 v208, v198, v208
	v_add_f32_e32 v208, v206, v208
	s_waitcnt lgkmcnt(0)
	v_mfma_f32_32x32x16_bf16 v[32:47], v[174:177], v[84:87], v[32:47]
	v_add_f32_e32 v208, v199, v208
	v_add_f32_e32 v88, v207, v208
	s_setprio 0
	s_cmpk_lg_i32 s8, 0x7f
	s_mov_b32 s44, s9
	s_mov_b32 s9, s41
	s_barrier
	s_cbranch_scc1 .LBB0_629
	ds_read_b128 v[64:67], v90 offset:49152
	ds_read_b128 v[68:71], v90 offset:49184
	ds_read_b128 v[72:75], v90 offset:53760
	ds_read_b128 v[76:79], v90 offset:53792
	ds_read_b128 v[80:83], v90 offset:49216
	ds_read_b128 v[84:87], v90 offset:49248
	ds_read_b128 v[92:95], v90 offset:53824
	ds_read_b128 v[96:99], v90 offset:53856
	v_exp_f32_e32 v89, v48
	v_exp_f32_e32 v90, v49
	v_exp_f32_e32 v91, v50
	v_exp_f32_e32 v100, v51
	v_exp_f32_e32 v52, v52
	v_exp_f32_e32 v53, v53
	v_exp_f32_e32 v54, v54
	v_exp_f32_e32 v55, v55
	v_cvt_pk_bf16_f32 v48, v89, v90
	v_cvt_pk_bf16_f32 v49, v91, v100
	v_cvt_pk_bf16_f32 v50, v52, v53
	v_cvt_pk_bf16_f32 v51, v54, v55
	v_exp_f32_e32 v56, v56
	v_exp_f32_e32 v57, v57
	s_waitcnt lgkmcnt(7)
	v_mfma_f32_32x32x16_bf16 v[16:31], v[64:67], v[48:51], v[16:31]
	v_exp_f32_e32 v58, v58
	v_exp_f32_e32 v59, v59
	v_exp_f32_e32 v60, v60
	v_exp_f32_e32 v61, v61
	v_exp_f32_e32 v62, v62
	v_exp_f32_e32 v63, v63
	v_exp_f32_e32 v64, v32
	s_waitcnt lgkmcnt(5)
	v_mfma_f32_32x32x16_bf16 v[0:15], v[72:75], v[48:51], v[0:15]
	v_cvt_pk_bf16_f32 v48, v56, v57
	v_cvt_pk_bf16_f32 v49, v58, v59
	v_cvt_pk_bf16_f32 v50, v60, v61
	v_cvt_pk_bf16_f32 v51, v62, v63
	v_exp_f32_e32 v65, v33
	v_exp_f32_e32 v66, v34
	v_exp_f32_e32 v67, v35
	v_mfma_f32_32x32x16_bf16 v[16:31], v[68:71], v[48:51], v[16:31]
	v_exp_f32_e32 v36, v36
	v_exp_f32_e32 v37, v37
	v_exp_f32_e32 v38, v38
	v_exp_f32_e32 v39, v39
	v_cvt_pk_bf16_f32 v32, v64, v65
	v_cvt_pk_bf16_f32 v33, v66, v67
	v_cvt_pk_bf16_f32 v34, v36, v37
	s_waitcnt lgkmcnt(4)
	v_mfma_f32_32x32x16_bf16 v[0:15], v[76:79], v[48:51], v[0:15]
	v_cvt_pk_bf16_f32 v35, v38, v39
	v_add_f32_e32 v48, v88, v89
	v_add_f32_e32 v48, v64, v48
	v_exp_f32_e32 v40, v40
	v_exp_f32_e32 v41, v41
	v_exp_f32_e32 v42, v42
	v_exp_f32_e32 v43, v43
	s_waitcnt lgkmcnt(3)
	v_mfma_f32_32x32x16_bf16 v[16:31], v[80:83], v[32:35], v[16:31]
	v_exp_f32_e32 v44, v44
	v_exp_f32_e32 v45, v45
	v_exp_f32_e32 v46, v46
	v_exp_f32_e32 v47, v47
	v_add_f32_e32 v48, v90, v48
	v_add_f32_e32 v48, v65, v48
	v_add_f32_e32 v48, v91, v48
	s_waitcnt lgkmcnt(1)
	v_mfma_f32_32x32x16_bf16 v[0:15], v[92:95], v[32:35], v[0:15]
	v_add_f32_e32 v48, v66, v48
	v_cvt_pk_bf16_f32 v32, v40, v41
	v_cvt_pk_bf16_f32 v33, v42, v43
	v_cvt_pk_bf16_f32 v34, v44, v45
	v_cvt_pk_bf16_f32 v35, v46, v47
	v_add_f32_e32 v48, v100, v48
	s_mov_b64 s[44:45], 0
	v_mfma_f32_32x32x16_bf16 v[16:31], v[84:87], v[32:35], v[16:31]
	s_waitcnt lgkmcnt(0)
	s_barrier
	v_mfma_f32_32x32x16_bf16 v[0:15], v[96:99], v[32:35], v[0:15]
	v_add_f32_e32 v32, v67, v48
	v_add_f32_e32 v32, v52, v32
	v_add_f32_e32 v32, v36, v32
	v_add_f32_e32 v32, v53, v32
	v_add_f32_e32 v32, v37, v32
	v_add_f32_e32 v32, v54, v32
	v_add_f32_e32 v32, v38, v32
	v_add_f32_e32 v32, v55, v32
	v_add_f32_e32 v32, v39, v32
	v_add_f32_e32 v32, v56, v32
	v_add_f32_e32 v32, v40, v32
	v_add_f32_e32 v32, v57, v32
	v_add_f32_e32 v32, v41, v32
	v_add_f32_e32 v32, v58, v32
	v_add_f32_e32 v32, v42, v32
	v_add_f32_e32 v32, v59, v32
	v_add_f32_e32 v32, v43, v32
	v_add_f32_e32 v32, v60, v32
	v_add_f32_e32 v32, v44, v32
	v_add_f32_e32 v32, v61, v32
	v_add_f32_e32 v32, v45, v32
	v_add_f32_e32 v32, v62, v32
	v_add_f32_e32 v32, v46, v32
	v_add_f32_e32 v32, v63, v32
	v_add_f32_e32 v32, v47, v32
	v_mov_b32_e32 v33, v32
	s_nop 1
	v_permlane32_swap_b32_e32 v32, v33
.LBB0_631:
	s_and_b64 vcc, exec, s[44:45]
	s_cbranch_vccz .LBB0_592
	s_add_i32 s8, s60, 2
	s_add_i32 s9, s40, 0x2000
	s_mul_i32 s41, s38, 0x180000
	s_lshl_b64 s[46:47], s[38:39], 20
	s_mul_hi_i32 s22, s38, 0x180000
	s_add_u32 s44, s6, s41
	v_mbcnt_lo_u32_b32 v39, -1, 0
	v_mbcnt_hi_u32_b32 v39, -1, v39
	s_addc_u32 s45, s7, s22
	v_add_u32_e32 v32, s33, v39
	s_mul_i32 s59, s59, 0xc000
	v_and_b32_e32 v40, 0xff, v32
	s_add_u32 s60, s44, s59
	v_lshlrev_b32_e32 v36, 4, v40
	v_mov_b32_e32 v37, v169
	s_addc_u32 s61, s45, 0
	v_lshl_add_u64 v[28:29], s[60:61], 0, v[36:37]
	v_add_co_u32_e32 v8, vcc, s54, v28
	s_add_u32 s46, s12, s46
	v_lshlrev_b32_e32 v0, 7, v39
	v_addc_co_u32_e32 v9, vcc, 0, v29, vcc
	s_addc_u32 s47, s13, s47
	v_bfe_u32 v41, v32, 6, 2
	v_and_b32_e32 v12, 0x1f80, v0
	global_load_dwordx4 v[0:3], v36, s[60:61]
	s_add_u32 s60, s46, s40
	v_add_co_u32_e32 v24, vcc, s55, v28
	v_lshl_or_b32 v38, v41, 4, v12
	s_addc_u32 s61, s47, 0
	v_addc_co_u32_e32 v25, vcc, 0, v29, vcc
	global_load_dwordx4 v[4:7], v[8:9], off offset:-4096
	s_nop 0
	global_load_dwordx4 v[8:11], v[8:9], off
	s_nop 0
	global_load_dwordx4 v[12:15], v38, s[60:61]
	global_load_dwordx4 v[16:19], v38, s[60:61] offset:64
	global_load_dwordx4 v[20:23], v[24:25], off offset:-4096
	s_nop 0
	global_load_dwordx4 v[24:27], v[24:25], off
	v_ashrrev_i32_e32 v32, 1, v32
	v_and_b32_e32 v168, 31, v39
	v_and_b32_e32 v170, 0xffffffe0, v32
	v_ashrrev_i32_e32 v171, 31, v170
	v_or_b32_e32 v32, s42, v168
	v_mov_b32_e32 v33, s43
	v_lshl_add_u64 v[32:33], v[32:33], 0, v[170:171]
	v_mov_b64_e32 v[34:35], s[0:1]
	v_mad_u64_u32 v[34:35], s[42:43], v32, s35, v[34:35]
	v_mov_b32_e32 v32, v35
	v_bfe_u32 v172, v39, 5, 1
	v_mad_u64_u32 v[32:33], s[42:43], v33, s35, v[32:33]
	v_add_co_u32_e32 v28, vcc, s56, v28
	v_mov_b32_e32 v35, v32
	v_lshlrev_b32_e32 v32, 4, v172
	v_mov_b32_e32 v33, v169
	v_addc_co_u32_e32 v29, vcc, 0, v29, vcc
	v_lshl_add_u64 v[34:35], v[34:35], 0, v[32:33]
	global_load_dwordx4 v[28:31], v[28:29], off
	s_nop 0
	global_load_dwordx4 v[84:87], v[34:35], off
	global_load_dwordx4 v[80:83], v[34:35], off offset:32
	global_load_dwordx4 v[76:79], v[34:35], off offset:64
	global_load_dwordx4 v[72:75], v[34:35], off offset:96
	global_load_dwordx4 v[68:71], v[34:35], off offset:128
	global_load_dwordx4 v[64:67], v[34:35], off offset:160
	v_mul_lo_u16_e32 v33, 0xab, v40
	v_lshrrev_b16_e32 v33, 11, v33
	v_add_lshl_u32 v160, v40, v33, 4
	v_or_b32_e32 v33, 0x100, v40
	v_mul_u32_u24_e32 v34, 0x1556, v33
	v_lshrrev_b32_e32 v34, 16, v34
	v_add_lshl_u32 v161, v33, v34, 4
	v_or_b32_e32 v33, 0x200, v40
	v_mul_u32_u24_e32 v34, 0x1556, v33
	v_lshrrev_b32_e32 v34, 16, v34
	v_add_lshl_u32 v162, v33, v34, 4
	v_lshrrev_b32_e32 v34, 1, v39
	v_lshlrev_b32_e32 v35, 1, v39
	v_and_b32_e32 v33, 51, v39
	v_and_b32_e32 v34, 4, v34
	v_and_b32_e32 v35, 8, v35
	v_or3_b32 v33, v33, v34, v35
	v_lshlrev_b32_e32 v33, 1, v33
	v_mul_u32_u24_e32 v34, 0x480, v41
	v_add_u32_e32 v35, 0, v160
	v_add3_u32 v156, 0, v33, v34
	v_mov_b32_e32 v39, v169
	v_mov_b32_e32 v159, 0
	s_mov_b32 s59, 2
	s_mov_b32 s39, 1
	s_mov_b32 s41, 0
	v_lshl_add_u64 v[154:155], s[44:45], 0, v[36:37]
	v_lshl_add_u64 v[152:153], s[46:47], 0, v[38:39]
	s_mov_b32 s42, 0
	s_waitcnt vmcnt(13)
	ds_write_b128 v35, v[0:3]
	v_add_u32_e32 v0, 0, v161
	v_add_u32_e32 v1, 0, v162
	v_mov_b32_e32 v2, v159
	v_mov_b32_e32 v3, v159
	s_waitcnt vmcnt(12)
	ds_write_b128 v0, v[4:7]
	s_waitcnt vmcnt(11)
	ds_write_b128 v1, v[8:11]
	s_waitcnt vmcnt(10)
	ds_write_b16 v156, v12 offset:39936
	ds_write_b16_d16_hi v156, v12 offset:40080
	ds_write_b16 v156, v13 offset:40224
	ds_write_b16_d16_hi v156, v13 offset:40368
	ds_write_b16 v156, v14 offset:40512
	ds_write_b16_d16_hi v156, v14 offset:40656
	ds_write_b16 v156, v15 offset:40800
	ds_write_b16_d16_hi v156, v15 offset:40944
	s_waitcnt vmcnt(9)
	ds_write_b16 v156, v16 offset:44544
	ds_write_b16_d16_hi v156, v16 offset:44688
	ds_write_b16 v156, v17 offset:44832
	ds_write_b16_d16_hi v156, v17 offset:44976
	ds_write_b16 v156, v18 offset:45120
	ds_write_b16_d16_hi v156, v18 offset:45264
	ds_write_b16 v156, v19 offset:45408
	ds_write_b16_d16_hi v156, v19 offset:45552
	s_waitcnt vmcnt(8)
	ds_write_b128 v35, v[20:23] offset:13312
	s_waitcnt vmcnt(7)
	ds_write_b128 v0, v[24:27] offset:13312
	s_waitcnt vmcnt(6)
	ds_write_b128 v1, v[28:31] offset:13312
	v_mul_u32_u24_e32 v0, 0xd0, v168
	v_add3_u32 v158, 0, v0, v32
	s_waitcnt lgkmcnt(0)
	s_barrier
	ds_read_b128 v[32:35], v158
	ds_read_b128 v[116:119], v158 offset:32
	ds_read_b128 v[128:131], v158 offset:6656
	ds_read_b128 v[124:127], v158 offset:6688
	ds_read_b128 v[112:115], v158 offset:64
	ds_read_b128 v[100:103], v158 offset:96
	ds_read_b128 v[108:111], v158 offset:6720
	ds_read_b128 v[104:107], v158 offset:6752
	ds_read_b128 v[92:95], v158 offset:128
	ds_read_b128 v[88:91], v158 offset:160
	ds_read_b128 v[120:123], v158 offset:6784
	ds_read_b128 v[96:99], v158 offset:6816
	v_lshlrev_b32_e32 v0, 6, v168
	v_sub_u32_e32 v157, v158, v0
	v_mov_b32_e32 v16, 0
	v_mov_b32_e32 v17, v159
	v_mov_b32_e32 v18, v159
	v_mov_b32_e32 v19, v159
	v_mov_b32_e32 v20, v159
	v_mov_b32_e32 v21, v159
	v_mov_b32_e32 v22, v159
	v_mov_b32_e32 v23, v159
	v_mov_b32_e32 v24, v159
	v_mov_b32_e32 v25, v159
	v_mov_b32_e32 v26, v159
	v_mov_b32_e32 v27, v159
	v_mov_b32_e32 v28, v159
	v_mov_b32_e32 v29, v159
	v_mov_b32_e32 v30, v159
	v_mov_b32_e32 v31, v159
	v_mov_b32_e32 v0, 0
	v_mov_b32_e32 v1, v159
	v_mov_b32_e32 v4, v159
	v_mov_b32_e32 v5, v159
	v_mov_b32_e32 v6, v159
	v_mov_b32_e32 v7, v159
	v_mov_b32_e32 v8, v159
	v_mov_b32_e32 v9, v159
	v_mov_b32_e32 v10, v159
	v_mov_b32_e32 v11, v159
	v_mov_b32_e32 v12, v159
	v_mov_b32_e32 v13, v159
	v_mov_b32_e32 v14, v159
	v_mov_b32_e32 v15, v159
	v_mov_b32_e32 v163, v159
	v_mov_b32_e32 v173, v159
	v_mov_b32_e32 v190, v159
	v_mov_b32_e32 v191, v159
	v_mov_b32_e32 v192, v159
	v_mov_b32_e32 v193, v159
	v_mov_b32_e32 v194, v159
	v_mov_b32_e32 v195, v159
	v_mov_b32_e32 v196, v159
	v_mov_b32_e32 v197, v159
	v_mov_b32_e32 v198, v159
	v_mov_b32_e32 v199, v159
	v_mov_b32_e32 v200, v159
	v_mov_b32_e32 v201, v159
	v_mov_b32_e32 v202, v159
	v_mov_b32_e32 v203, v159
	v_mov_b32_e32 v204, v159
	v_mov_b32_e32 v205, v159
	v_mov_b32_e32 v206, v159
	v_mov_b32_e32 v207, v159
	v_mov_b32_e32 v208, v159
	v_mov_b32_e32 v209, v159
	v_mov_b32_e32 v210, v159
	v_mov_b32_e32 v211, v159
	v_mov_b32_e32 v212, v159
	v_mov_b32_e32 v213, v159
	v_mov_b32_e32 v214, v159
	v_mov_b32_e32 v215, v159
	v_mov_b32_e32 v216, v159
	v_mov_b32_e32 v217, v159
	v_mov_b32_e32 v218, v159
	v_mov_b32_e32 v219, v159
.LBB0_633:
	s_add_i32 s22, s8, s41
	s_and_b32 s22, s22, 0x7f
	s_mulk_i32 s22, 0x3000
	v_lshl_add_u64 v[36:37], v[154:155], 0, s[22:23]
	global_load_dwordx4 v[140:143], v[36:37], off
	v_add_co_u32_e32 v36, vcc, s54, v36
	s_and_b32 s22, s9, 0xfe000
	s_nop 0
	v_addc_co_u32_e32 v37, vcc, 0, v37, vcc
	v_lshl_add_u64 v[38:39], v[152:153], 0, s[22:23]
	global_load_dwordx4 v[144:147], v[36:37], off
	global_load_dwordx4 v[136:139], v[38:39], off
	global_load_dwordx4 v[148:151], v[36:37], off offset:-4096
	global_load_dwordx4 v[132:135], v[38:39], off offset:64
	s_mov_b32 s22, s39
	s_mov_b32 s39, s59
	s_and_b32 s44, s41, 1
	s_add_i32 s41, s41, 1
	s_setprio 1
	s_waitcnt vmcnt(10) lgkmcnt(11)
	v_mfma_f32_32x32x16_bf16 v[32:47], v[32:35], v[84:87], 0
	v_add_f32_e32 v220, v163, v159
	v_add_f32_e32 v220, v204, v220
	v_add_f32_e32 v220, v173, v220
	s_waitcnt lgkmcnt(9)
	v_mfma_f32_32x32x16_bf16 v[48:63], v[128:131], v[84:87], 0
	v_add_f32_e32 v220, v205, v220
	v_add_f32_e32 v220, v190, v220
	v_add_f32_e32 v220, v206, v220
	s_waitcnt vmcnt(9)
	v_mfma_f32_32x32x16_bf16 v[32:47], v[116:119], v[80:83], v[32:47]
	v_add_f32_e32 v220, v191, v220
	v_add_f32_e32 v220, v207, v220
	v_add_f32_e32 v220, v192, v220
	s_waitcnt lgkmcnt(8)
	v_mfma_f32_32x32x16_bf16 v[48:63], v[124:127], v[80:83], v[48:63]
	v_add_f32_e32 v220, v208, v220
	v_add_f32_e32 v220, v193, v220
	v_add_f32_e32 v220, v209, v220
	s_waitcnt vmcnt(8) lgkmcnt(7)
	v_mfma_f32_32x32x16_bf16 v[32:47], v[112:115], v[76:79], v[32:47]
	v_add_f32_e32 v220, v194, v220
	v_add_f32_e32 v220, v210, v220
	v_add_f32_e32 v220, v195, v220
	s_waitcnt lgkmcnt(5)
	v_mfma_f32_32x32x16_bf16 v[48:63], v[108:111], v[76:79], v[48:63]
	v_add_f32_e32 v220, v211, v220
	v_add_f32_e32 v220, v196, v220
	v_add_f32_e32 v220, v212, v220
	s_waitcnt vmcnt(7)
	v_mfma_f32_32x32x16_bf16 v[32:47], v[100:103], v[72:75], v[32:47]
	v_add_f32_e32 v220, v197, v220
	v_add_f32_e32 v220, v213, v220
	v_add_f32_e32 v220, v198, v220
	s_waitcnt lgkmcnt(4)
	v_mfma_f32_32x32x16_bf16 v[48:63], v[104:107], v[72:75], v[48:63]
	v_add_f32_e32 v220, v214, v220
	v_add_f32_e32 v220, v199, v220
	v_add_f32_e32 v220, v215, v220
	s_waitcnt vmcnt(6) lgkmcnt(3)
	v_mfma_f32_32x32x16_bf16 v[32:47], v[92:95], v[68:71], v[32:47]
	v_add_f32_e32 v220, v200, v220
	v_add_f32_e32 v220, v216, v220
	s_waitcnt lgkmcnt(1)
	v_mfma_f32_32x32x16_bf16 v[48:63], v[120:123], v[68:71], v[48:63]
	v_add_f32_e32 v220, v201, v220
	v_add_f32_e32 v220, v217, v220
	s_waitcnt vmcnt(5)
	v_mfma_f32_32x32x16_bf16 v[32:47], v[88:91], v[64:67], v[32:47]
	v_add_f32_e32 v220, v202, v220
	v_add_f32_e32 v220, v218, v220
	s_waitcnt lgkmcnt(0)
	v_mfma_f32_32x32x16_bf16 v[48:63], v[96:99], v[64:67], v[48:63]
	v_add_f32_e32 v220, v203, v220
	v_add_f32_e32 v159, v219, v220
	s_setprio 0
	s_mul_i32 s43, s44, 0x2400
	v_add_u32_e32 v100, s43, v157
	ds_read_b128 v[88:91], v100 offset:39936
	ds_read_b128 v[96:99], v100 offset:39968
	ds_read_b128 v[92:95], v100 offset:44544
	ds_read_b128 v[164:167], v100 offset:44576
	ds_read_b128 v[174:177], v100 offset:40000
	ds_read_b128 v[178:181], v100 offset:40032
	ds_read_b128 v[182:185], v100 offset:44608
	ds_read_b128 v[186:189], v100 offset:44640
	v_exp_f32_e32 v163, v32
	v_exp_f32_e32 v173, v33
	v_exp_f32_e32 v190, v34
	v_exp_f32_e32 v191, v35
	v_exp_f32_e32 v192, v36
	v_exp_f32_e32 v193, v37
	v_exp_f32_e32 v194, v38
	v_exp_f32_e32 v195, v39
	v_cvt_pk_bf16_f32 v36, v163, v173
	v_cvt_pk_bf16_f32 v37, v190, v191
	v_cvt_pk_bf16_f32 v38, v192, v193
	v_cvt_pk_bf16_f32 v39, v194, v195
	v_exp_f32_e32 v196, v40
	v_exp_f32_e32 v197, v41
	s_waitcnt lgkmcnt(7)
	v_mfma_f32_32x32x16_bf16 v[16:31], v[88:91], v[36:39], v[16:31]
	v_exp_f32_e32 v198, v42
	v_exp_f32_e32 v199, v43
	v_exp_f32_e32 v200, v44
	v_exp_f32_e32 v201, v45
	v_exp_f32_e32 v202, v46
	v_exp_f32_e32 v203, v47
	v_exp_f32_e32 v204, v48
	s_waitcnt lgkmcnt(5)
	v_mfma_f32_32x32x16_bf16 v[0:15], v[92:95], v[36:39], v[0:15]
	v_exp_f32_e32 v205, v49
	s_mul_i32 s43, s22, 0x3400
	v_add_u32_e32 v40, s43, v158
	v_cvt_pk_bf16_f32 v36, v196, v197
	v_cvt_pk_bf16_f32 v37, v198, v199
	v_cvt_pk_bf16_f32 v38, v200, v201
	v_cvt_pk_bf16_f32 v39, v202, v203
	v_exp_f32_e32 v206, v50
	ds_read_b128 v[32:35], v40
	ds_read_b128 v[116:119], v40 offset:32
	ds_read_b128 v[128:131], v40 offset:6656
	ds_read_b128 v[124:127], v40 offset:6688
	ds_read_b128 v[108:111], v40 offset:6720
	ds_read_b128 v[112:115], v40 offset:64
	ds_read_b128 v[100:103], v40 offset:96
	ds_read_b128 v[104:107], v40 offset:6752
	ds_read_b128 v[92:95], v40 offset:128
	ds_read_b128 v[88:91], v40 offset:160
	v_mfma_f32_32x32x16_bf16 v[16:31], v[96:99], v[36:39], v[16:31]
	ds_read_b128 v[120:123], v40 offset:6784
	ds_read_b128 v[96:99], v40 offset:6816
	v_cvt_pk_bf16_f32 v40, v204, v205
	v_exp_f32_e32 v207, v51
	s_waitcnt lgkmcnt(14)
	v_mfma_f32_32x32x16_bf16 v[0:15], v[164:167], v[36:39], v[0:15]
	v_exp_f32_e32 v208, v52
	v_exp_f32_e32 v209, v53
	v_exp_f32_e32 v210, v54
	v_exp_f32_e32 v211, v55
	v_cvt_pk_bf16_f32 v41, v206, v207
	v_cvt_pk_bf16_f32 v42, v208, v209
	v_cvt_pk_bf16_f32 v43, v210, v211
	v_exp_f32_e32 v212, v56
	v_exp_f32_e32 v213, v57
	v_mfma_f32_32x32x16_bf16 v[16:31], v[174:177], v[40:43], v[16:31]
	v_exp_f32_e32 v214, v58
	v_exp_f32_e32 v215, v59
	v_exp_f32_e32 v216, v60
	v_exp_f32_e32 v217, v61
	v_exp_f32_e32 v218, v62
	v_exp_f32_e32 v219, v63
	s_waitcnt lgkmcnt(13)
	v_mfma_f32_32x32x16_bf16 v[0:15], v[182:185], v[40:43], v[0:15]
	v_cvt_pk_bf16_f32 v36, v212, v213
	v_cvt_pk_bf16_f32 v37, v214, v215
	v_cvt_pk_bf16_f32 v38, v216, v217
	v_cvt_pk_bf16_f32 v39, v218, v219
	s_nop 1
	v_mfma_f32_32x32x16_bf16 v[16:31], v[178:181], v[36:39], v[16:31]
	s_waitcnt lgkmcnt(12)
	v_mfma_f32_32x32x16_bf16 v[0:15], v[186:189], v[36:39], v[0:15]
	s_mul_i32 s43, s59, 0x3400
	s_xor_b32 s44, s44, 1
	s_addk_i32 s9, 0x2000
	s_mov_b32 s59, s42
	s_mov_b32 s42, s22
	s_add_i32 s22, s43, 0
	s_mulk_i32 s44, 0x2400
	v_add_u32_e32 v38, s22, v160
	s_cmpk_lg_i32 s41, 0x7e
	v_add_u32_e32 v36, s22, v162
	v_add_u32_e32 v37, s22, v161
	v_add_u32_e32 v39, s44, v156
	s_waitcnt vmcnt(4)
	ds_write_b128 v38, v[140:143]
	s_waitcnt vmcnt(1)
	ds_write_b128 v37, v[148:151]
	ds_write_b128 v36, v[144:147]
	ds_write_b16 v39, v136 offset:39936
	ds_write_b16_d16_hi v39, v136 offset:40080
	ds_write_b16 v39, v137 offset:40224
	ds_write_b16_d16_hi v39, v137 offset:40368
	ds_write_b16 v39, v138 offset:40512
	ds_write_b16_d16_hi v39, v138 offset:40656
	ds_write_b16 v39, v139 offset:40800
	ds_write_b16_d16_hi v39, v139 offset:40944
	s_waitcnt vmcnt(0)
	ds_write_b16 v39, v132 offset:44544
	ds_write_b16_d16_hi v39, v132 offset:44688
	ds_write_b16 v39, v133 offset:44832
	ds_write_b16_d16_hi v39, v133 offset:44976
	ds_write_b16 v39, v134 offset:45120
	ds_write_b16_d16_hi v39, v134 offset:45264
	ds_write_b16 v39, v135 offset:45408
	ds_write_b16_d16_hi v39, v135 offset:45552
	s_waitcnt lgkmcnt(0)
	s_barrier
	s_cbranch_scc1 .LBB0_633
	s_add_i32 s8, s40, 0xfe000
	s_and_b32 s22, s8, 0xfe000
	v_lshl_add_u64 v[36:37], v[152:153], 0, s[22:23]
	global_load_dwordx4 v[132:135], v[36:37], off
	global_load_dwordx4 v[136:139], v[36:37], off offset:64
	s_setprio 1
	v_mfma_f32_32x32x16_bf16 v[48:63], v[32:35], v[84:87], 0
	v_add_f32_e32 v220, v163, v159
	v_add_f32_e32 v220, v204, v220
	v_add_f32_e32 v220, v173, v220
	v_mfma_f32_32x32x16_bf16 v[32:47], v[128:131], v[84:87], 0
	v_add_f32_e32 v220, v205, v220
	v_add_f32_e32 v220, v190, v220
	v_add_f32_e32 v220, v206, v220
	v_mfma_f32_32x32x16_bf16 v[32:47], v[124:127], v[80:83], v[32:47]
	v_add_f32_e32 v220, v191, v220
	v_add_f32_e32 v220, v207, v220
	v_add_f32_e32 v220, v192, v220
	v_mfma_f32_32x32x16_bf16 v[48:63], v[116:119], v[80:83], v[48:63]
	v_add_f32_e32 v220, v208, v220
	v_add_f32_e32 v220, v193, v220
	v_add_f32_e32 v220, v209, v220
	v_mfma_f32_32x32x16_bf16 v[32:47], v[108:111], v[76:79], v[32:47]
	v_add_f32_e32 v220, v194, v220
	v_add_f32_e32 v220, v210, v220
	v_add_f32_e32 v220, v195, v220
	v_mfma_f32_32x32x16_bf16 v[48:63], v[112:115], v[76:79], v[48:63]
	v_add_f32_e32 v220, v211, v220
	v_add_f32_e32 v220, v196, v220
	v_add_f32_e32 v220, v212, v220
	v_mfma_f32_32x32x16_bf16 v[32:47], v[104:107], v[72:75], v[32:47]
	v_add_f32_e32 v220, v197, v220
	v_add_f32_e32 v220, v213, v220
	v_add_f32_e32 v220, v198, v220
	v_mfma_f32_32x32x16_bf16 v[48:63], v[100:103], v[72:75], v[48:63]
	v_add_f32_e32 v220, v214, v220
	v_add_f32_e32 v220, v199, v220
	v_add_f32_e32 v220, v215, v220
	v_mfma_f32_32x32x16_bf16 v[32:47], v[120:123], v[68:71], v[32:47]
	v_add_f32_e32 v220, v200, v220
	v_add_f32_e32 v220, v216, v220
	v_mfma_f32_32x32x16_bf16 v[48:63], v[92:95], v[68:71], v[48:63]
	v_add_f32_e32 v220, v201, v220
	v_add_f32_e32 v220, v217, v220
	v_mfma_f32_32x32x16_bf16 v[32:47], v[96:99], v[64:67], v[32:47]
	v_add_f32_e32 v220, v202, v220
	v_add_f32_e32 v220, v218, v220
	v_mfma_f32_32x32x16_bf16 v[48:63], v[88:91], v[64:67], v[48:63]
	v_add_f32_e32 v220, v203, v220
	v_add_f32_e32 v159, v219, v220
	s_setprio 0
	ds_read_b128 v[88:91], v157 offset:39936
	ds_read_b128 v[92:95], v157 offset:39968
	ds_read_b128 v[96:99], v157 offset:44544
	ds_read_b128 v[100:103], v157 offset:44576
	ds_read_b128 v[104:107], v157 offset:40000
	ds_read_b128 v[108:111], v157 offset:40032
	ds_read_b128 v[112:115], v157 offset:44608
	ds_read_b128 v[116:119], v157 offset:44640
	s_nop 2
	v_exp_f32_e32 v140, v48
	v_exp_f32_e32 v141, v49
	v_exp_f32_e32 v142, v50
	v_exp_f32_e32 v143, v51
	v_exp_f32_e32 v52, v52
	v_exp_f32_e32 v53, v53
	v_exp_f32_e32 v54, v54
	v_exp_f32_e32 v55, v55
	v_cvt_pk_bf16_f32 v48, v140, v141
	v_cvt_pk_bf16_f32 v49, v142, v143
	v_cvt_pk_bf16_f32 v50, v52, v53
	v_cvt_pk_bf16_f32 v51, v54, v55
	v_exp_f32_e32 v56, v56
	v_exp_f32_e32 v57, v57
	s_waitcnt lgkmcnt(7)
	v_mfma_f32_32x32x16_bf16 v[16:31], v[88:91], v[48:51], v[16:31]
	v_exp_f32_e32 v58, v58
	v_exp_f32_e32 v59, v59
	v_exp_f32_e32 v60, v60
	v_exp_f32_e32 v61, v61
	v_exp_f32_e32 v62, v62
	v_exp_f32_e32 v63, v63
	v_exp_f32_e32 v144, v32
	s_waitcnt lgkmcnt(5)
	v_mfma_f32_32x32x16_bf16 v[0:15], v[96:99], v[48:51], v[0:15]
	v_cvt_pk_bf16_f32 v48, v56, v57
	v_cvt_pk_bf16_f32 v49, v58, v59
	v_cvt_pk_bf16_f32 v50, v60, v61
	v_cvt_pk_bf16_f32 v51, v62, v63
	v_exp_f32_e32 v145, v33
	v_exp_f32_e32 v146, v34
	v_exp_f32_e32 v147, v35
	v_mfma_f32_32x32x16_bf16 v[16:31], v[92:95], v[48:51], v[16:31]
	v_exp_f32_e32 v148, v36
	v_cvt_pk_bf16_f32 v32, v144, v145
	v_cvt_pk_bf16_f32 v33, v146, v147
	v_exp_f32_e32 v149, v41
	v_exp_f32_e32 v150, v42
	v_exp_f32_e32 v151, v43
	v_exp_f32_e32 v44, v44
	s_waitcnt lgkmcnt(4)
	v_mfma_f32_32x32x16_bf16 v[0:15], v[100:103], v[48:51], v[0:15]
	v_exp_f32_e32 v48, v37
	v_exp_f32_e32 v49, v38
	v_exp_f32_e32 v50, v39
	v_exp_f32_e32 v51, v40
	v_cvt_pk_bf16_f32 v34, v148, v48
	v_exp_f32_e32 v45, v45
	v_cvt_pk_bf16_f32 v35, v49, v50
	v_exp_f32_e32 v46, v46
	v_exp_f32_e32 v47, v47
	s_waitcnt lgkmcnt(3)
	v_mfma_f32_32x32x16_bf16 v[16:31], v[104:107], v[32:35], v[16:31]
	v_add_u32_e32 v128, s43, v158
	s_waitcnt lgkmcnt(1)
	v_mfma_f32_32x32x16_bf16 v[0:15], v[112:115], v[32:35], v[0:15]
	v_cvt_pk_bf16_f32 v32, v51, v149
	v_cvt_pk_bf16_f32 v33, v150, v151
	v_cvt_pk_bf16_f32 v34, v44, v45
	v_cvt_pk_bf16_f32 v35, v46, v47
	s_nop 1
	v_mfma_f32_32x32x16_bf16 v[16:31], v[108:111], v[32:35], v[16:31]
	ds_read_b128 v[36:39], v128
	ds_read_b128 v[88:91], v128 offset:32
	ds_read_b128 v[40:43], v128 offset:6656
	ds_read_b128 v[92:95], v128 offset:6688
	ds_read_b128 v[96:99], v128 offset:64
	ds_read_b128 v[100:103], v128 offset:96
	ds_read_b128 v[104:107], v128 offset:6720
	ds_read_b128 v[108:111], v128 offset:6752
	ds_read_b128 v[112:115], v128 offset:128
	ds_read_b128 v[120:123], v128 offset:160
	ds_read_b128 v[124:127], v128 offset:6784
	ds_read_b128 v[128:131], v128 offset:6816
	s_waitcnt lgkmcnt(12)
	v_mfma_f32_32x32x16_bf16 v[0:15], v[116:119], v[32:35], v[0:15]
	v_add_f32_e32 v32, v159, v140
	v_add_f32_e32 v32, v144, v32
	v_add_f32_e32 v32, v141, v32
	v_add_f32_e32 v32, v145, v32
	v_add_f32_e32 v32, v142, v32
	v_add_f32_e32 v32, v146, v32
	v_add_f32_e32 v32, v143, v32
	v_add_f32_e32 v32, v147, v32
	v_add_f32_e32 v32, v52, v32
	v_add_f32_e32 v32, v148, v32
	v_add_f32_e32 v32, v53, v32
	v_add_f32_e32 v32, v48, v32
	v_add_f32_e32 v32, v54, v32
	v_add_f32_e32 v32, v49, v32
	v_add_f32_e32 v32, v55, v32
	v_add_f32_e32 v32, v50, v32
	v_add_f32_e32 v32, v56, v32
	v_add_f32_e32 v32, v51, v32
	v_add_f32_e32 v32, v57, v32
	v_add_f32_e32 v32, v149, v32
	v_add_f32_e32 v32, v58, v32
	v_add_f32_e32 v32, v150, v32
	v_add_f32_e32 v32, v59, v32
	v_add_f32_e32 v32, v151, v32
	v_add_f32_e32 v32, v60, v32
	v_add_f32_e32 v32, v44, v32
	v_add_f32_e32 v32, v61, v32
	v_add_f32_e32 v32, v45, v32
	v_add_f32_e32 v32, v62, v32
	v_add_f32_e32 v32, v46, v32
	v_add_f32_e32 v32, v63, v32
	v_add_f32_e32 v116, v47, v32
	s_waitcnt vmcnt(1)
	ds_write_b16 v156, v132 offset:49152
	ds_write_b16_d16_hi v156, v132 offset:49296
	ds_write_b16 v156, v133 offset:49440
	ds_write_b16_d16_hi v156, v133 offset:49584
	ds_write_b16 v156, v134 offset:49728
	ds_write_b16_d16_hi v156, v134 offset:49872
	ds_write_b16 v156, v135 offset:50016
	ds_write_b16_d16_hi v156, v135 offset:50160
	s_waitcnt vmcnt(0)
	ds_write_b16 v156, v136 offset:53760
	ds_write_b16_d16_hi v156, v136 offset:53904
	ds_write_b16 v156, v137 offset:54048
	ds_write_b16_d16_hi v156, v137 offset:54192
	ds_write_b16 v156, v138 offset:54336
	ds_write_b16_d16_hi v156, v138 offset:54480
	ds_write_b16 v156, v139 offset:54624
	ds_write_b16_d16_hi v156, v139 offset:54768
	s_waitcnt lgkmcnt(0)
	s_barrier
	s_setprio 1
	v_mfma_f32_32x32x16_bf16 v[48:63], v[36:39], v[84:87], 0
	v_mfma_f32_32x32x16_bf16 v[32:47], v[40:43], v[84:87], 0
	v_mfma_f32_32x32x16_bf16 v[32:47], v[92:95], v[80:83], v[32:47]
	v_mfma_f32_32x32x16_bf16 v[48:63], v[88:91], v[80:83], v[48:63]
	v_mfma_f32_32x32x16_bf16 v[32:47], v[104:107], v[76:79], v[32:47]
	v_mfma_f32_32x32x16_bf16 v[48:63], v[96:99], v[76:79], v[48:63]
	v_mfma_f32_32x32x16_bf16 v[32:47], v[108:111], v[72:75], v[32:47]
	v_mfma_f32_32x32x16_bf16 v[48:63], v[100:103], v[72:75], v[48:63]
	v_mfma_f32_32x32x16_bf16 v[32:47], v[124:127], v[68:71], v[32:47]
	v_mfma_f32_32x32x16_bf16 v[48:63], v[112:115], v[68:71], v[48:63]
	v_mfma_f32_32x32x16_bf16 v[32:47], v[128:131], v[64:67], v[32:47]
	v_mfma_f32_32x32x16_bf16 v[48:63], v[120:123], v[64:67], v[48:63]
	s_setprio 0
	ds_read_b128 v[64:67], v157 offset:49152
	ds_read_b128 v[68:71], v157 offset:49184
	ds_read_b128 v[72:75], v157 offset:53760
	ds_read_b128 v[76:79], v157 offset:53792
	ds_read_b128 v[80:83], v157 offset:49216
	ds_read_b128 v[84:87], v157 offset:49248
	ds_read_b128 v[88:91], v157 offset:53824
	ds_read_b128 v[92:95], v157 offset:53856
	s_nop 2
	v_exp_f32_e32 v96, v48
	v_exp_f32_e32 v97, v49
	v_exp_f32_e32 v98, v50
	v_exp_f32_e32 v99, v51
	v_exp_f32_e32 v52, v52
	v_exp_f32_e32 v53, v53
	v_exp_f32_e32 v54, v54
	v_exp_f32_e32 v55, v55
	v_cvt_pk_bf16_f32 v48, v96, v97
	v_cvt_pk_bf16_f32 v49, v98, v99
	v_cvt_pk_bf16_f32 v50, v52, v53
	v_cvt_pk_bf16_f32 v51, v54, v55
	v_exp_f32_e32 v56, v56
	v_exp_f32_e32 v57, v57
	s_waitcnt lgkmcnt(7)
	v_mfma_f32_32x32x16_bf16 v[16:31], v[64:67], v[48:51], v[16:31]
	v_exp_f32_e32 v58, v58
	v_exp_f32_e32 v59, v59
	v_exp_f32_e32 v60, v60
	v_exp_f32_e32 v61, v61
	v_exp_f32_e32 v62, v62
	v_exp_f32_e32 v63, v63
	v_exp_f32_e32 v64, v32
	s_waitcnt lgkmcnt(5)
	v_mfma_f32_32x32x16_bf16 v[0:15], v[72:75], v[48:51], v[0:15]
	v_cvt_pk_bf16_f32 v48, v56, v57
	v_cvt_pk_bf16_f32 v49, v58, v59
	v_cvt_pk_bf16_f32 v50, v60, v61
	v_cvt_pk_bf16_f32 v51, v62, v63
	v_exp_f32_e32 v65, v33
	v_exp_f32_e32 v66, v34
	v_exp_f32_e32 v67, v35
	v_mfma_f32_32x32x16_bf16 v[16:31], v[68:71], v[48:51], v[16:31]
	v_exp_f32_e32 v36, v36
	v_exp_f32_e32 v37, v37
	v_exp_f32_e32 v38, v38
	v_exp_f32_e32 v39, v39
	v_cvt_pk_bf16_f32 v32, v64, v65
	v_cvt_pk_bf16_f32 v33, v66, v67
	v_cvt_pk_bf16_f32 v34, v36, v37
	s_waitcnt lgkmcnt(4)
	v_mfma_f32_32x32x16_bf16 v[0:15], v[76:79], v[48:51], v[0:15]
	v_cvt_pk_bf16_f32 v35, v38, v39
	v_add_f32_e32 v48, v116, v96
	v_add_f32_e32 v48, v64, v48
	v_exp_f32_e32 v40, v40
	v_exp_f32_e32 v41, v41
	v_exp_f32_e32 v42, v42
	v_exp_f32_e32 v43, v43
	s_waitcnt lgkmcnt(3)
	v_mfma_f32_32x32x16_bf16 v[16:31], v[80:83], v[32:35], v[16:31]
	v_exp_f32_e32 v44, v44
	v_exp_f32_e32 v45, v45
	v_exp_f32_e32 v46, v46
	v_exp_f32_e32 v47, v47
	v_add_f32_e32 v48, v97, v48
	v_add_f32_e32 v48, v65, v48
	v_add_f32_e32 v48, v98, v48
	s_waitcnt lgkmcnt(1)
	v_mfma_f32_32x32x16_bf16 v[0:15], v[88:91], v[32:35], v[0:15]
	v_add_f32_e32 v48, v66, v48
	v_cvt_pk_bf16_f32 v32, v40, v41
	v_cvt_pk_bf16_f32 v33, v42, v43
	v_cvt_pk_bf16_f32 v34, v44, v45
	v_cvt_pk_bf16_f32 v35, v46, v47
	v_add_f32_e32 v48, v99, v48
	s_waitcnt lgkmcnt(0)
	v_mfma_f32_32x32x16_bf16 v[16:31], v[84:87], v[32:35], v[16:31]
	s_barrier
	v_mfma_f32_32x32x16_bf16 v[0:15], v[92:95], v[32:35], v[0:15]
	v_add_f32_e32 v32, v67, v48
	v_add_f32_e32 v32, v52, v32
	v_add_f32_e32 v32, v36, v32
	v_add_f32_e32 v32, v53, v32
	v_add_f32_e32 v32, v37, v32
	v_add_f32_e32 v32, v54, v32
	v_add_f32_e32 v32, v38, v32
	v_add_f32_e32 v32, v55, v32
	v_add_f32_e32 v32, v39, v32
	v_add_f32_e32 v32, v56, v32
	v_add_f32_e32 v32, v40, v32
	v_add_f32_e32 v32, v57, v32
	v_add_f32_e32 v32, v41, v32
	v_add_f32_e32 v32, v58, v32
	v_add_f32_e32 v32, v42, v32
	v_add_f32_e32 v32, v59, v32
	v_add_f32_e32 v32, v43, v32
	v_add_f32_e32 v32, v60, v32
	v_add_f32_e32 v32, v44, v32
	v_add_f32_e32 v32, v61, v32
	v_add_f32_e32 v32, v45, v32
	v_add_f32_e32 v32, v62, v32
	v_add_f32_e32 v32, v46, v32
	v_add_f32_e32 v32, v63, v32
	v_add_f32_e32 v32, v47, v32
	v_mov_b32_e32 v33, v32
	s_nop 1
	v_permlane32_swap_b32_e32 v32, v33
	s_branch .LBB0_592
